# top-k search: one pre-test (key>=64) jumps straight to the low 6 bits when fewer than 16 causal blocks exist
# baseline (speedup 1.0000x reference)
.LBB0_1145:
	s_or_b64 exec, exec, s[8:9]
	v_and_b32_e32 v34, 0xffffffc0, v37
	v_add_u32_e32 v34, v34, v40
	v_cndmask_b32_e64 v34, v34, v39, s[0:1]
	v_cndmask_b32_e64 v47, v34, v41, s[6:7]
	s_mov_b32 s14, 0
	v_cmp_le_u32_e64 s[10:11], 64, v47
	s_bcnt1_i32_b64 s8, s[10:11]
	s_cmp_eq_u32 s8, 16
	s_cbranch_scc1 .Ltk_done
	s_cmp_lt_u32 s8, 16
	s_cbranch_scc1 .Ltk_low
	s_or_b32 s15, s14, 0x80000000
	v_cmp_le_u32_e64 s[10:11], s15, v47
	s_bcnt1_i32_b64 s8, s[10:11]
	s_cmp_eq_u32 s8, 16
	s_cbranch_scc1 .Ltk_done
	s_cmp_gt_u32 s8, 15
	s_cselect_b32 s14, s15, s14
	s_or_b32 s15, s14, 0x40000000
	v_cmp_le_u32_e64 s[10:11], s15, v47
	s_bcnt1_i32_b64 s8, s[10:11]
	s_cmp_eq_u32 s8, 16
	s_cbranch_scc1 .Ltk_done
	s_cmp_gt_u32 s8, 15
	s_cselect_b32 s14, s15, s14
	s_or_b32 s15, s14, 0x20000000
	v_cmp_le_u32_e64 s[10:11], s15, v47
	s_bcnt1_i32_b64 s8, s[10:11]
	s_cmp_eq_u32 s8, 16
	s_cbranch_scc1 .Ltk_done
	s_cmp_gt_u32 s8, 15
	s_cselect_b32 s14, s15, s14
	s_or_b32 s15, s14, 0x10000000
	v_cmp_le_u32_e64 s[10:11], s15, v47
	s_bcnt1_i32_b64 s8, s[10:11]
	s_cmp_eq_u32 s8, 16
	s_cbranch_scc1 .Ltk_done
	s_cmp_gt_u32 s8, 15
	s_cselect_b32 s14, s15, s14
	s_or_b32 s15, s14, 0x8000000
	v_cmp_le_u32_e64 s[10:11], s15, v47
	s_bcnt1_i32_b64 s8, s[10:11]
	s_cmp_eq_u32 s8, 16
	s_cbranch_scc1 .Ltk_done
	s_cmp_gt_u32 s8, 15
	s_cselect_b32 s14, s15, s14
	s_or_b32 s15, s14, 0x4000000
	v_cmp_le_u32_e64 s[10:11], s15, v47
	s_bcnt1_i32_b64 s8, s[10:11]
	s_cmp_eq_u32 s8, 16
	s_cbranch_scc1 .Ltk_done
	s_cmp_gt_u32 s8, 15
	s_cselect_b32 s14, s15, s14
	s_or_b32 s15, s14, 0x2000000
	v_cmp_le_u32_e64 s[10:11], s15, v47
	s_bcnt1_i32_b64 s8, s[10:11]
	s_cmp_eq_u32 s8, 16
	s_cbranch_scc1 .Ltk_done
	s_cmp_gt_u32 s8, 15
	s_cselect_b32 s14, s15, s14
	s_or_b32 s15, s14, 0x1000000
	v_cmp_le_u32_e64 s[10:11], s15, v47
	s_bcnt1_i32_b64 s8, s[10:11]
	s_cmp_eq_u32 s8, 16
	s_cbranch_scc1 .Ltk_done
	s_cmp_gt_u32 s8, 15
	s_cselect_b32 s14, s15, s14
	s_or_b32 s15, s14, 0x800000
	v_cmp_le_u32_e64 s[10:11], s15, v47
	s_bcnt1_i32_b64 s8, s[10:11]
	s_cmp_eq_u32 s8, 16
	s_cbranch_scc1 .Ltk_done
	s_cmp_gt_u32 s8, 15
	s_cselect_b32 s14, s15, s14
	s_or_b32 s15, s14, 0x400000
	v_cmp_le_u32_e64 s[10:11], s15, v47
	s_bcnt1_i32_b64 s8, s[10:11]
	s_cmp_eq_u32 s8, 16
	s_cbranch_scc1 .Ltk_done
	s_cmp_gt_u32 s8, 15
	s_cselect_b32 s14, s15, s14
	s_or_b32 s15, s14, 0x200000
	v_cmp_le_u32_e64 s[10:11], s15, v47
	s_bcnt1_i32_b64 s8, s[10:11]
	s_cmp_eq_u32 s8, 16
	s_cbranch_scc1 .Ltk_done
	s_cmp_gt_u32 s8, 15
	s_cselect_b32 s14, s15, s14
	s_or_b32 s15, s14, 0x100000
	v_cmp_le_u32_e64 s[10:11], s15, v47
	s_bcnt1_i32_b64 s8, s[10:11]
	s_cmp_eq_u32 s8, 16
	s_cbranch_scc1 .Ltk_done
	s_cmp_gt_u32 s8, 15
	s_cselect_b32 s14, s15, s14
	s_or_b32 s15, s14, 0x80000
	v_cmp_le_u32_e64 s[10:11], s15, v47
	s_bcnt1_i32_b64 s8, s[10:11]
	s_cmp_eq_u32 s8, 16
	s_cbranch_scc1 .Ltk_done
	s_cmp_gt_u32 s8, 15
	s_cselect_b32 s14, s15, s14
	s_or_b32 s15, s14, 0x40000
	v_cmp_le_u32_e64 s[10:11], s15, v47
	s_bcnt1_i32_b64 s8, s[10:11]
	s_cmp_eq_u32 s8, 16
	s_cbranch_scc1 .Ltk_done
	s_cmp_gt_u32 s8, 15
	s_cselect_b32 s14, s15, s14
	s_or_b32 s15, s14, 0x20000
	v_cmp_le_u32_e64 s[10:11], s15, v47
	s_bcnt1_i32_b64 s8, s[10:11]
	s_cmp_eq_u32 s8, 16
	s_cbranch_scc1 .Ltk_done
	s_cmp_gt_u32 s8, 15
	s_cselect_b32 s14, s15, s14
	s_or_b32 s15, s14, 0x10000
	v_cmp_le_u32_e64 s[10:11], s15, v47
	s_bcnt1_i32_b64 s8, s[10:11]
	s_cmp_eq_u32 s8, 16
	s_cbranch_scc1 .Ltk_done
	s_cmp_gt_u32 s8, 15
	s_cselect_b32 s14, s15, s14
	s_or_b32 s15, s14, 0x8000
	v_cmp_le_u32_e64 s[10:11], s15, v47
	s_bcnt1_i32_b64 s8, s[10:11]
	s_cmp_eq_u32 s8, 16
	s_cbranch_scc1 .Ltk_done
	s_cmp_gt_u32 s8, 15
	s_cselect_b32 s14, s15, s14
	s_or_b32 s15, s14, 0x4000
	v_cmp_le_u32_e64 s[10:11], s15, v47
	s_bcnt1_i32_b64 s8, s[10:11]
	s_cmp_eq_u32 s8, 16
	s_cbranch_scc1 .Ltk_done
	s_cmp_gt_u32 s8, 15
	s_cselect_b32 s14, s15, s14
	s_or_b32 s15, s14, 0x2000
	v_cmp_le_u32_e64 s[10:11], s15, v47
	s_bcnt1_i32_b64 s8, s[10:11]
	s_cmp_eq_u32 s8, 16
	s_cbranch_scc1 .Ltk_done
	s_cmp_gt_u32 s8, 15
	s_cselect_b32 s14, s15, s14
	s_or_b32 s15, s14, 0x1000
	v_cmp_le_u32_e64 s[10:11], s15, v47
	s_bcnt1_i32_b64 s8, s[10:11]
	s_cmp_eq_u32 s8, 16
	s_cbranch_scc1 .Ltk_done
	s_cmp_gt_u32 s8, 15
	s_cselect_b32 s14, s15, s14
	s_or_b32 s15, s14, 0x800
	v_cmp_le_u32_e64 s[10:11], s15, v47
	s_bcnt1_i32_b64 s8, s[10:11]
	s_cmp_eq_u32 s8, 16
	s_cbranch_scc1 .Ltk_done
	s_cmp_gt_u32 s8, 15
	s_cselect_b32 s14, s15, s14
	s_or_b32 s15, s14, 0x400
	v_cmp_le_u32_e64 s[10:11], s15, v47
	s_bcnt1_i32_b64 s8, s[10:11]
	s_cmp_eq_u32 s8, 16
	s_cbranch_scc1 .Ltk_done
	s_cmp_gt_u32 s8, 15
	s_cselect_b32 s14, s15, s14
	s_or_b32 s15, s14, 0x200
	v_cmp_le_u32_e64 s[10:11], s15, v47
	s_bcnt1_i32_b64 s8, s[10:11]
	s_cmp_eq_u32 s8, 16
	s_cbranch_scc1 .Ltk_done
	s_cmp_gt_u32 s8, 15
	s_cselect_b32 s14, s15, s14
	s_or_b32 s15, s14, 0x100
	v_cmp_le_u32_e64 s[10:11], s15, v47
	s_bcnt1_i32_b64 s8, s[10:11]
	s_cmp_eq_u32 s8, 16
	s_cbranch_scc1 .Ltk_done
	s_cmp_gt_u32 s8, 15
	s_cselect_b32 s14, s15, s14
	s_or_b32 s15, s14, 0x80
	v_cmp_le_u32_e64 s[10:11], s15, v47
	s_bcnt1_i32_b64 s8, s[10:11]
	s_cmp_eq_u32 s8, 16
	s_cbranch_scc1 .Ltk_done
	s_cmp_gt_u32 s8, 15
	s_cselect_b32 s14, s15, s14
	s_or_b32 s15, s14, 64
	v_cmp_le_u32_e64 s[10:11], s15, v47
	s_bcnt1_i32_b64 s8, s[10:11]
	s_cmp_eq_u32 s8, 16
	s_cbranch_scc1 .Ltk_done
	s_cmp_gt_u32 s8, 15
	s_cselect_b32 s14, s15, s14
.Ltk_low:
	s_or_b32 s15, s14, 32
	v_cmp_le_u32_e64 s[10:11], s15, v47
	s_bcnt1_i32_b64 s8, s[10:11]
	s_cmp_eq_u32 s8, 16
	s_cbranch_scc1 .Ltk_done
	s_cmp_gt_u32 s8, 15
	s_cselect_b32 s14, s15, s14
	s_or_b32 s15, s14, 16
	v_cmp_le_u32_e64 s[10:11], s15, v47
	s_bcnt1_i32_b64 s8, s[10:11]
	s_cmp_eq_u32 s8, 16
	s_cbranch_scc1 .Ltk_done
	s_cmp_gt_u32 s8, 15
	s_cselect_b32 s14, s15, s14
	s_or_b32 s15, s14, 8
	v_cmp_le_u32_e64 s[10:11], s15, v47
	s_bcnt1_i32_b64 s8, s[10:11]
	s_cmp_eq_u32 s8, 16
	s_cbranch_scc1 .Ltk_done
	s_cmp_gt_u32 s8, 15
	s_cselect_b32 s14, s15, s14
	s_or_b32 s15, s14, 4
	v_cmp_le_u32_e64 s[10:11], s15, v47
	s_bcnt1_i32_b64 s8, s[10:11]
	s_cmp_eq_u32 s8, 16
	s_cbranch_scc1 .Ltk_done
	s_cmp_gt_u32 s8, 15
	s_cselect_b32 s14, s15, s14
	s_or_b32 s15, s14, 2
	v_cmp_le_u32_e64 s[10:11], s15, v47
	s_bcnt1_i32_b64 s8, s[10:11]
	s_cmp_eq_u32 s8, 16
	s_cbranch_scc1 .Ltk_done
	s_cmp_gt_u32 s8, 15
	s_cselect_b32 s14, s15, s14
	s_or_b32 s15, s14, 1
	v_cmp_le_u32_e64 s[10:11], s15, v47
	s_bcnt1_i32_b64 s8, s[10:11]
	s_cmp_eq_u32 s8, 16
	s_cbranch_scc1 .Ltk_done
	s_cmp_gt_u32 s8, 15
	s_cselect_b32 s14, s15, s14
	v_cmp_le_u32_e64 s[10:11], s14, v47
